# attention: waves 4-7 start each KV stage one QK block late (s_sleep 8) so SIMD partners alternate MFMA and softmax VALU
# baseline (speedup 1.0000x reference)
.LBB0_306:
	v_readfirstlane_b32 s99, v244
	s_cmp_lt_u32 s99, 0x100
	s_cbranch_scc1 .Lstag0
	s_sleep 8
